# base20 + finish (E) row loop: next-row prefetch no longer waited at the loop head; one counted wait before the latch copies
# baseline (speedup 1.0000x reference)
; __device__ __forceinline__ void phase_finish(const Args& a, const WCtx& w, int l, int nrows) {
;     const bf16* ZB = (const bf16*)(a.ws + WS_ZB); const bf16* PB = (const bf16*)(a.ws + WS_PB); const bf16* SO = (const bf16*)(a.ws + WS_SO); const float* FO = (const float*)(a.ws + WS_FO);
;     bf16* OUTS = (bf16*)(a.ws + WS_OUTS);
;     const int ch = 4 * w.lane, hd = w.lane >> 4;
;     const f32x4 nwa = *(const f32x4*)(a.in[I_HGRN_NW] + l * 256 + ch), nwb = *(const f32x4*)(a.in[I_GDN_NW] + l * 256 + ch), nwd = *(const f32x4*)(a.in[I_SSD_NW] + l * 256 + ch);
;     const float dsk = a.in[I_SSD_D][l * 4 + hd];
;     int row = w.gw; FinRow R, Rn;
;     if (row < nrows) fin_load(R, ZB, PB, SO, FO, row, ch);
;     while (row < nrows) {
;         const int nrow = row + w.NGW;
;         if (nrow < nrows) fin_load(Rn, ZB, PB, SO, FO, nrow, ch);
.LBB0_1711:
	s_andn2_b64 vcc, exec, s[0:1]
	s_cbranch_vccnz .LBB0_1771
	v_mov_b32_e32 v10, v0
	v_readlane_b32 s0, v252, 0
	v_readlane_b32 s2, v254, 60
	v_readfirstlane_b32 s1, v10
	s_ashr_i32 s1, s1, 6
	s_lshl_b32 s0, s0, 3
	v_readlane_b32 s3, v254, 61
	s_add_i32 s0, s0, s1
	s_load_dword s10, s[2:3], 0x0
	s_mov_b64 s[2:3], s[52:53]
	s_cmp_ge_i32 s0, s19
	s_waitcnt lgkmcnt(0)
	s_cbranch_scc1 .LBB0_1717
	v_readlane_b32 s1, v255, 7
	v_readlane_b32 s4, v254, 32
	v_readlane_b32 s5, v254, 33
	s_lshl_b32 s4, s1, 8
	s_lshl_b32 s2, s10, 3
	s_mov_b32 s3, s5
	s_lshl_b64 s[4:5], s[4:5], 2
	v_readlane_b32 s56, v252, 25
	v_readlane_b32 s57, v252, 26
	s_add_u32 s6, s56, s4
	v_readlane_b32 s64, v252, 33
	s_addc_u32 s7, s57, s5
	v_and_b32_e32 v12, 63, v10
	v_writelane_b32 v254, s2, 32
	v_readlane_b32 s65, v252, 34
	s_add_u32 s8, s64, s4
	v_writelane_b32 v254, s3, 33
	s_waitcnt vmcnt(0)
	v_lshlrev_b32_e32 v28, 4, v12
	s_addc_u32 s9, s65, s5
	v_bfe_u32 v10, v10, 4, 2
	global_load_dwordx4 v[2:5], v28, s[6:7] nt
	global_load_dwordx4 v[6:9], v28, s[8:9] nt
	s_add_u32 s4, s76, s4
	v_lshl_or_b32 v10, s1, 2, v10
	v_mov_b32_e32 v11, v51
	v_readlane_b32 s6, v254, 5
	s_addc_u32 s5, s77, s5
	v_lshl_add_u64 v[10:11], v[10:11], 2, s[74:75]
	s_ashr_i32 s1, s0, 31
	v_lshlrev_b32_e32 v14, 3, v12
	v_mov_b32_e32 v15, v51
	v_readlane_b32 s7, v254, 6
	global_load_dword v22, v[10:11], off nt
	s_mov_b32 s3, 0x1200000
	v_lshl_add_u64 v[10:11], s[6:7], 0, v[14:15]
	s_lshl_b64 s[6:7], s[0:1], 9
	v_lshl_add_u64 v[10:11], v[10:11], 0, s[6:7]
	v_add_co_u32_e32 v12, vcc, s3, v10
	s_mov_b32 s3, 0x2400000
	s_nop 0
	v_addc_co_u32_e32 v13, vcc, 0, v11, vcc
	v_add_co_u32_e32 v16, vcc, s3, v10
	s_mov_b32 s3, 0x3600000
	s_nop 0
	v_addc_co_u32_e32 v17, vcc, 0, v11, vcc
	v_add_co_u32_e32 v18, vcc, s3, v10
	s_mov_b32 s3, 0x4800000
	s_nop 0
	v_addc_co_u32_e32 v19, vcc, 0, v11, vcc
	global_load_dwordx2 v[76:77], v[10:11], off nt
	global_load_dwordx2 v[74:75], v[12:13], off nt
	global_load_dwordx2 v[68:69], v[16:17], off nt
	global_load_dwordx2 v[70:71], v[18:19], off nt
	v_add_co_u32_e32 v12, vcc, s3, v10
	s_mov_b32 s3, 0x5a00000
	s_nop 0
	v_addc_co_u32_e32 v13, vcc, 0, v11, vcc
	s_mul_i32 s6, s0, 0x1600
	v_readlane_b32 s8, v253, 41
	v_add_co_u32_e32 v10, vcc, s3, v10
	s_mul_hi_i32 s3, s0, 0x1600
	v_readlane_b32 s9, v253, 42
	s_add_u32 s6, s8, s6
	s_addc_u32 s7, s9, s3
	v_addc_co_u32_e32 v11, vcc, 0, v11, vcc
	v_lshl_add_u64 v[16:17], s[6:7], 0, v[14:15]
	s_movk_i32 s3, 0x1000
	s_mul_i32 s8, s0, 0xa00
	v_readlane_b32 s12, v253, 43
	v_add_co_u32_e32 v16, vcc, s3, v16
	s_mul_hi_i32 s3, s0, 0xa00
	v_readlane_b32 s13, v253, 44
	s_add_u32 s8, s12, s8
	s_addc_u32 s9, s13, s3
	v_addc_co_u32_e32 v17, vcc, 0, v17, vcc
	global_load_dwordx2 v[52:53], v[12:13], off nt
	global_load_dwordx2 v[48:49], v[10:11], off nt
	global_load_dwordx2 v[72:73], v14, s[6:7] offset:1024 nt
	global_load_dwordx2 v[36:37], v[16:17], off offset:1024 nt
	global_load_dwordx2 v[66:67], v14, s[6:7] offset:3072 nt
	global_load_dwordx2 v[38:39], v14, s[8:9] offset:1536 nt
	s_lshl_b64 s[6:7], s[0:1], 10
	v_readlane_b32 s8, v253, 47
	v_readlane_b32 s9, v253, 48
	s_add_u32 s6, s8, s6
	s_addc_u32 s7, s9, s7
	global_load_dwordx4 v[10:13], v28, s[4:5] nt
	global_load_dwordx4 v[18:21], v28, s[6:7] nt
	s_add_i32 s12, s0, s2
	s_lshl_b64 s[4:5], s[0:1], 11
	s_ashr_i32 s3, s2, 31
	s_ashr_i32 s13, s12, 31
	v_or_b32_e32 v24, s4, v14
	v_mov_b32_e32 v25, s5
	s_lshl_b64 s[4:5], s[2:3], 11
	s_lshl_b64 s[6:7], s[12:13], 10
	s_add_u32 s1, s6, 0x38800000
	s_addc_u32 s6, s7, 0
	v_mov_b32_e32 v29, s6
	s_lshl_b64 s[6:7], s[2:3], 10
	s_mul_i32 s8, s12, 0xa00
	v_or_b32_e32 v28, s1, v28
	s_mul_hi_i32 s1, s12, 0xa00
	s_add_u32 s8, s8, 0x29e00600
	v_readlane_b32 s58, v252, 27
	v_readlane_b32 s59, v252, 28
	v_readlane_b32 s60, v252, 29
	v_readlane_b32 s61, v252, 30
	s_addc_u32 s1, s1, 0
	v_readlane_b32 s62, v252, 31
	v_readlane_b32 s63, v252, 32
	v_readlane_b32 s68, v252, 37
	v_readlane_b32 s69, v252, 38
	v_readlane_b32 s70, v252, 39
	v_readlane_b32 s71, v252, 40
	s_mov_b32 s58, 0x3f6c835e
	v_readlane_b32 s60, v255, 2
	v_mov_b32_e32 v31, s1
	s_mul_hi_i32 s1, s12, 0x1600
	s_mul_i32 s11, s12, 0x1600
	s_lshl_b64 s[12:13], s[12:13], 9
	s_mov_b32 s63, 0xbf6c835e
	v_readlane_b32 s62, v255, 4
	s_movk_i32 s68, 0x2200
	s_movk_i32 s71, 0x1ff
	s_mov_b32 s69, 0x7f800000
	s_movk_i32 s70, 0x4000
	s_mov_b32 s59, 0xbec3ef15
	v_readlane_b32 s61, v255, 3
	s_movk_i32 s64, 0x440
	s_waitcnt vmcnt(12)
	v_mov_b32_e32 v23, v22
	v_mov_b32_e32 v26, v22
	v_mov_b32_e32 v27, v22
	v_or_b32_e32 v30, s8, v14
	s_mul_i32 s8, s10, 0x5000
	s_mul_hi_i32 s9, s2, 0xa00
	v_or_b32_e32 v32, s11, v14
	v_mov_b32_e32 v33, s1
	s_mul_i32 s10, s10, 0xb000
	s_mul_hi_i32 s11, s2, 0x1600
	v_or_b32_e32 v34, s12, v14
	v_mov_b32_e32 v35, s13
	s_lshl_b64 s[12:13], s[2:3], 9
	v_readlane_b32 s66, v252, 35
	v_readlane_b32 s67, v252, 36
	s_waitcnt vmcnt(0)
	s_branch .LBB0_1715
; __device__ __forceinline__ float dpp_x7(float x) { return __int_as_float(__builtin_amdgcn_mov_dpp(__float_as_int(x), 0x141, 0xf, 0xf, true)); }
; __device__ __forceinline__ float dpp_x15(float x) { return __int_as_float(__builtin_amdgcn_mov_dpp(__float_as_int(x), 0x140, 0xf, 0xf, true)); }
; __device__ __forceinline__ float dpp_xor1(float x) { return __int_as_float(__builtin_amdgcn_mov_dpp(__float_as_int(x), 0xB1, 0xf, 0xf, true)); }
; __device__ __forceinline__ float dpp_xor2(float x) { return __int_as_float(__builtin_amdgcn_mov_dpp(__float_as_int(x), 0x4E, 0xf, 0xf, true)); }
; __device__ __forceinline__ void st_bf4(bf16* p, f32x4 v) { v2u w; w.x = cvt_pk_bf16(v[0], v[1]); w.y = cvt_pk_bf16(v[2], v[3]); *(v2u*)p = w; }
; __device__ __forceinline__ f32x4 silu4f(f32x4 x) { return (f32x4){x[0] * sigmoid_fast(x[0]), x[1] * sigmoid_fast(x[1]), x[2] * sigmoid_fast(x[2]), x[3] * sigmoid_fast(x[3])}; }
; __device__ __forceinline__ void phase_finish(const Args& a, const WCtx& w, int l, int nrows) {
;     ...
;     while (row < nrows) {
;         const int nrow = row + w.NGW;
;         if (nrow < nrows) fin_load(Rn, ZB, PB, SO, FO, nrow, ch);
;         asm volatile("" ::: "memory");
;         bf16* orow = OUTS + (size_t)row * 1024 + ch;
;         { f32x4 o = bf4(R.so[0]) + bf4(R.so[1]);
;           float ss = (o[0] * o[0] + o[1] * o[1]) + (o[2] * o[2] + o[3] * o[3]); ss += dpp_xor1(ss); ss += dpp_xor2(ss); ss += dpp_x7(ss); ss += dpp_x15(ss);
;           const float r = __builtin_amdgcn_rsqf(ss * (1.f / 64.f) + LN_EPS); st_bf4(orow, o * r * nwa * silu4f(bf4(R.zg[0]))); }
;         { f32x4 o = bf4(R.so[2]) + bf4(R.so[3]);
;           float ss = (o[0] * o[0] + o[1] * o[1]) + (o[2] * o[2] + o[3] * o[3]); ss += dpp_xor1(ss); ss += dpp_xor2(ss); ss += dpp_x7(ss); ss += dpp_x15(ss);
;           const float r = __builtin_amdgcn_rsqf(ss * (1.f / 64.f) + LN_EPS); st_bf4(orow + 256, o * r * nwb * silu4f(bf4(R.zg[1]))); }
;         st_bf4(orow + 512, R.fo0 + R.fo1);
;         { f32x4 o = bf4(R.so[4]) + bf4(R.so[5]); f32x4 y = (o + bf4(R.px) * dsk) * silu4f(bf4(R.zg[2]));
;           const float ss = wave_sum((y[0] * y[0] + y[1] * y[1]) + (y[2] * y[2] + y[3] * y[3]));
;           const float r = __builtin_amdgcn_rsqf(ss * (1.f / 256.f) + LN_EPS); st_bf4(orow + 768, y * r * nwd); }
.LBB0_1714:
	v_lshlrev_b32_e32 v78, 16, v76
	v_and_b32_e32 v79, 0xffff0000, v76
	v_lshlrev_b32_e32 v76, 16, v77
	v_and_b32_e32 v77, 0xffff0000, v77
	v_lshlrev_b32_e32 v80, 16, v74
	v_and_b32_e32 v81, 0xffff0000, v74
	v_lshlrev_b32_e32 v74, 16, v75
	v_and_b32_e32 v75, 0xffff0000, v75
	v_pk_add_f32 v[78:79], v[78:79], v[80:81]
	v_pk_add_f32 v[74:75], v[76:77], v[74:75]
	v_pk_mul_f32 v[80:81], v[78:79], v[78:79]
	v_pk_mul_f32 v[76:77], v[74:75], v[74:75]
	s_mov_b32 s1, 0x3d000000
	v_pk_mov_b32 v[82:83], v[80:81], v[76:77] op_sel:[1,0]
	v_mov_b32_e32 v81, v77
	v_pk_add_f32 v[76:77], v[82:83], v[80:81]
	v_lshlrev_b32_e32 v80, 16, v72
	v_add_f32_e32 v50, v76, v77
	v_and_b32_e32 v81, 0xffff0000, v72
	v_mul_f32_e32 v72, 0xbfb8aa3b, v80
	v_add_f32_dpp v50, v50, v50 quad_perm:[1,0,3,2] row_mask:0xf bank_mask:0xf bound_ctrl:1
	v_exp_f32_e32 v72, v72
	v_mul_f32_e32 v82, 0xbfb8aa3b, v81
	v_add_f32_dpp v50, v50, v50 quad_perm:[2,3,0,1] row_mask:0xf bank_mask:0xf bound_ctrl:1
	v_exp_f32_e32 v82, v82
	v_and_b32_e32 v83, 0xffff0000, v73
	v_add_f32_dpp v50, v50, v50 row_half_mirror row_mask:0xf bank_mask:0xf bound_ctrl:1
	v_lshl_add_u64 v[76:77], s[52:53], 0, v[24:25]
	v_pk_add_f32 v[18:19], v[18:19], 0 op_sel_hi:[1,0]
	v_add_f32_dpp v50, v50, v50 row_mirror row_mask:0xf bank_mask:0xf bound_ctrl:1
	v_fmamk_f32 v50, v50, 0x3c800000, v251
	v_rsq_f32_e32 v50, v50
	v_pk_add_f32 v[20:21], v[20:21], 0 op_sel_hi:[1,0]
	v_lshl_add_u64 v[24:25], v[24:25], 0, s[4:5]
	v_lshl_add_u64 v[28:29], v[28:29], 0, s[6:7]
	v_pk_mul_f32 v[74:75], v[74:75], v[50:51] op_sel_hi:[1,0]
	v_pk_mul_f32 v[78:79], v[78:79], v[50:51] op_sel_hi:[1,0]
	v_add_f32_e32 v50, 1.0, v72
	v_rcp_f32_e32 v72, v50
	v_add_f32_e32 v50, 1.0, v82
	v_lshlrev_b32_e32 v82, 16, v73
	v_mul_f32_e32 v73, 0xbfb8aa3b, v82
	v_exp_f32_e32 v84, v73
	v_mul_f32_e32 v73, 0xbfb8aa3b, v83
	v_exp_f32_e32 v85, v73
	v_rcp_f32_e32 v73, v50
	v_add_f32_e32 v50, 1.0, v84
	v_rcp_f32_e32 v84, v50
	v_add_f32_e32 v50, 1.0, v85
	v_rcp_f32_e32 v85, v50
	v_pk_mul_f32 v[78:79], v[2:3], v[78:79]
	v_pk_mul_f32 v[74:75], v[4:5], v[74:75]
	v_pk_mul_f32 v[72:73], v[72:73], v[80:81]
	v_pk_mul_f32 v[80:81], v[84:85], v[82:83]
	v_pk_mul_f32 v[72:73], v[72:73], v[78:79]
	v_pk_mul_f32 v[74:75], v[80:81], v[74:75]
	v_cvt_pk_bf16_f32 v72, v72, v73
	v_lshlrev_b32_e32 v78, 16, v70
	v_cvt_pk_bf16_f32 v73, v74, v75
	v_lshlrev_b32_e32 v74, 16, v68
	v_and_b32_e32 v75, 0xffff0000, v68
	v_lshlrev_b32_e32 v68, 16, v69
	v_and_b32_e32 v69, 0xffff0000, v69
	v_and_b32_e32 v79, 0xffff0000, v70
	v_lshlrev_b32_e32 v70, 16, v71
	v_and_b32_e32 v71, 0xffff0000, v71
	v_pk_add_f32 v[74:75], v[74:75], v[78:79]
	v_pk_add_f32 v[68:69], v[68:69], v[70:71]
	v_pk_mul_f32 v[78:79], v[74:75], v[74:75]
	v_pk_mul_f32 v[70:71], v[68:69], v[68:69]
	v_lshl_add_u64 v[30:31], v[30:31], 0, s[8:9]
	v_pk_mov_b32 v[80:81], v[78:79], v[70:71] op_sel:[1,0]
	v_mov_b32_e32 v79, v71
	v_pk_add_f32 v[70:71], v[80:81], v[78:79]
	v_lshl_add_u64 v[32:33], v[32:33], 0, s[10:11]
	v_add_f32_e32 v50, v70, v71
	v_add_co_u32_e32 v70, vcc, s1, v76
	s_nop 0
	v_add_f32_dpp v50, v50, v50 quad_perm:[1,0,3,2] row_mask:0xf bank_mask:0xf bound_ctrl:1
	v_addc_co_u32_e32 v71, vcc, 0, v77, vcc
	s_nop 0
	v_add_f32_dpp v50, v50, v50 quad_perm:[2,3,0,1] row_mask:0xf bank_mask:0xf bound_ctrl:1
	global_store_dwordx2 v[70:71], v[72:73], off
	v_lshlrev_b32_e32 v72, 16, v66
	v_add_f32_dpp v50, v50, v50 row_half_mirror row_mask:0xf bank_mask:0xf bound_ctrl:1
	v_and_b32_e32 v73, 0xffff0000, v66
	v_mul_f32_e32 v66, 0xbfb8aa3b, v72
	v_add_f32_dpp v50, v50, v50 row_mirror row_mask:0xf bank_mask:0xf bound_ctrl:1
	v_fmamk_f32 v50, v50, 0x3c800000, v251
	v_rsq_f32_e32 v50, v50
	v_exp_f32_e32 v66, v66
	v_mul_f32_e32 v76, 0xbfb8aa3b, v73
	v_exp_f32_e32 v76, v76
	v_pk_mul_f32 v[68:69], v[68:69], v[50:51] op_sel_hi:[1,0]
	v_pk_mul_f32 v[74:75], v[74:75], v[50:51] op_sel_hi:[1,0]
	v_add_f32_e32 v50, 1.0, v66
	v_rcp_f32_e32 v66, v50
	v_add_f32_e32 v50, 1.0, v76
	v_lshlrev_b32_e32 v76, 16, v67
	v_and_b32_e32 v77, 0xffff0000, v67
	v_mul_f32_e32 v67, 0xbfb8aa3b, v76
	v_exp_f32_e32 v78, v67
	v_mul_f32_e32 v67, 0xbfb8aa3b, v77
	v_exp_f32_e32 v79, v67
	v_rcp_f32_e32 v67, v50
	v_add_f32_e32 v50, 1.0, v78
	v_rcp_f32_e32 v78, v50
	v_add_f32_e32 v50, 1.0, v79
	v_rcp_f32_e32 v79, v50
	v_pk_mul_f32 v[74:75], v[6:7], v[74:75]
	v_pk_mul_f32 v[66:67], v[66:67], v[72:73]
	v_pk_mul_f32 v[68:69], v[8:9], v[68:69]
	v_pk_mul_f32 v[72:73], v[78:79], v[76:77]
	v_pk_mul_f32 v[66:67], v[66:67], v[74:75]
	v_pk_mul_f32 v[68:69], v[72:73], v[68:69]
	v_cvt_pk_bf16_f32 v66, v66, v67
	v_lshlrev_b32_e32 v72, 16, v37
	v_cvt_pk_bf16_f32 v67, v68, v69
	global_store_dwordx2 v[70:71], v[66:67], off offset:512
	v_lshlrev_b32_e32 v66, 16, v52
	v_and_b32_e32 v67, 0xffff0000, v52
	v_lshlrev_b32_e32 v52, 16, v53
	v_and_b32_e32 v53, 0xffff0000, v53
	v_lshlrev_b32_e32 v68, 16, v48
	v_and_b32_e32 v69, 0xffff0000, v48
	v_lshlrev_b32_e32 v48, 16, v49
	v_and_b32_e32 v49, 0xffff0000, v49
	v_pk_add_f32 v[48:49], v[52:53], v[48:49]
	v_pk_add_f32 v[52:53], v[66:67], v[68:69]
	v_and_b32_e32 v69, 0xffff0000, v36
	v_mul_f32_e32 v50, 0xbfb8aa3b, v69
	v_lshlrev_b32_e32 v68, 16, v36
	v_exp_f32_e32 v50, v50
	v_and_b32_e32 v73, 0xffff0000, v37
	v_mul_f32_e32 v37, 0xbfb8aa3b, v72
	v_mul_f32_e32 v36, 0xbfb8aa3b, v68
	v_exp_f32_e32 v74, v37
	v_mul_f32_e32 v37, 0xbfb8aa3b, v73
	v_exp_f32_e32 v36, v36
	v_exp_f32_e32 v75, v37
	v_add_f32_e32 v50, 1.0, v50
	v_rcp_f32_e32 v37, v50
	v_add_f32_e32 v50, 1.0, v74
	v_add_f32_e32 v36, 1.0, v36
	v_rcp_f32_e32 v74, v50
	v_add_f32_e32 v50, 1.0, v75
	v_rcp_f32_e32 v36, v36
	v_rcp_f32_e32 v75, v50
	v_lshlrev_b32_e32 v66, 16, v38
	v_and_b32_e32 v67, 0xffff0000, v38
	v_lshlrev_b32_e32 v38, 16, v39
	v_and_b32_e32 v39, 0xffff0000, v39
	v_pk_fma_f32 v[52:53], v[22:23], v[66:67], v[52:53]
	v_pk_fma_f32 v[38:39], v[26:27], v[38:39], v[48:49]
	v_pk_mul_f32 v[36:37], v[36:37], v[68:69]
	v_pk_mul_f32 v[48:49], v[74:75], v[72:73]
	v_pk_mul_f32 v[36:37], v[52:53], v[36:37]
	v_pk_mul_f32 v[38:39], v[38:39], v[48:49]
	v_mul_f32_e32 v48, v37, v37
	v_mul_f32_e32 v49, v39, v39
	v_fmac_f32_e32 v48, v36, v36
	v_fmac_f32_e32 v49, v38, v38
	v_add_f32_e32 v48, v48, v49
	v_cvt_pk_bf16_f32 v18, v18, v19
	v_cvt_pk_bf16_f32 v19, v20, v21
	global_store_dwordx2 v[70:71], v[18:19], off offset:1024
	v_lshl_add_u64 v[34:35], v[34:35], 0, s[12:13]
	v_add_f32_dpp v48, v48, v48 quad_perm:[1,0,3,2] row_mask:0xf bank_mask:0xf bound_ctrl:1
	s_andn2_b64 vcc, exec, s[14:15]
	s_waitcnt vmcnt(3)
; __device__ __forceinline__ void st_bf4(bf16* p, f32x4 v) { v2u w; w.x = cvt_pk_bf16(v[0], v[1]); w.y = cvt_pk_bf16(v[2], v[3]); *(v2u*)p = w; }
; __device__ __forceinline__ f32x4 silu4f(f32x4 x) { return (f32x4){x[0] * sigmoid_fast(x[0]), x[1] * sigmoid_fast(x[1]), x[2] * sigmoid_fast(x[2]), x[3] * sigmoid_fast(x[3])}; }
; __device__ __forceinline__ f32x4 bf4(v2u u) { return (f32x4){bf2f(u.x & 0xffffu), bf2f(u.x >> 16), bf2f(u.y & 0xffffu), bf2f(u.y >> 16)}; }
; __device__ __forceinline__ void phase_finish(const Args& a, const WCtx& w, int l, int nrows) {
;     ...
;         { f32x4 o = bf4(R.so[4]) + bf4(R.so[5]); f32x4 y = (o + bf4(R.px) * dsk) * silu4f(bf4(R.zg[2]));
;           const float ss = wave_sum((y[0] * y[0] + y[1] * y[1]) + (y[2] * y[2] + y[3] * y[3]));
;           const float r = __builtin_amdgcn_rsqf(ss * (1.f / 256.f) + LN_EPS); st_bf4(orow + 768, y * r * nwd); }
;         R = Rn; row = nrow;
	v_mov_b64_e32 v[76:77], v[40:41]
	v_add_f32_dpp v48, v48, v48 quad_perm:[2,3,0,1] row_mask:0xf bank_mask:0xf bound_ctrl:1
	v_mov_b64_e32 v[74:75], v[42:43]
	v_mov_b64_e32 v[68:69], v[44:45]
	v_add_f32_dpp v48, v48, v48 row_half_mirror row_mask:0xf bank_mask:0xf bound_ctrl:1
	v_mov_b64_e32 v[52:53], v[54:55]
	v_mov_b64_e32 v[72:73], v[58:59]
	v_add_f32_dpp v48, v48, v48 row_mirror row_mask:0xf bank_mask:0xf bound_ctrl:1
	v_mov_b32_e32 v49, v48
	s_nop 1
	v_permlane16_swap_b32_e32 v48, v49
	v_add_f32_e32 v48, v48, v49
	v_mov_b32_e32 v49, v48
	s_nop 1
	v_permlane32_swap_b32_e32 v48, v49
	v_add_f32_e32 v48, v48, v49
	v_fmamk_f32 v48, v48, 0x3b800000, v251
	v_rsq_f32_e32 v48, v48
	v_mov_b64_e32 v[66:67], v[60:61]
	v_pk_mul_f32 v[18:19], v[36:37], v[48:49] op_sel_hi:[1,0]
	v_pk_mul_f32 v[20:21], v[38:39], v[48:49] op_sel_hi:[1,0]
	v_pk_mul_f32 v[18:19], v[10:11], v[18:19]
	v_pk_mul_f32 v[20:21], v[12:13], v[20:21]
	v_cvt_pk_bf16_f32 v18, v18, v19
	v_mov_b64_e32 v[48:49], v[56:57]
	v_cvt_pk_bf16_f32 v19, v20, v21
	global_store_dwordx2 v[70:71], v[18:19], off offset:1536
	v_mov_b64_e32 v[20:21], v[16:17]
	v_mov_b64_e32 v[70:71], v[46:47]
	v_mov_b64_e32 v[36:37], v[62:63]
	v_mov_b64_e32 v[38:39], v[64:65]
	v_mov_b64_e32 v[18:19], v[14:15]
	s_cbranch_vccz .LBB0_1717
